# P3 v11: v6 + s_setprio 2 for the o/S compute waves over the staging waves during the scan
# speedup vs baseline: 1.0033x; 1.0023x over previous
; #define LAS __attribute__((address_space(3)))
; __device__ __forceinline__ void gla_scan_item(const Ctx& C, int item, LAS unsigned char* lds, int tid) {
;     const int jx = item >> 3, bh = (item & 7) * 4 + (jx >> 3), sl = jx & 7, b = bh >> 2, h = bh & 3;
;     LAS bf16* Aq = (LAS bf16*)lds;
;     LAS bf16* Bc = (LAS bf16*)(lds + 25600);
;     LAS bf16* Kt = (LAS bf16*)(lds + 38400);
;     const int wave = tid >> 6, lane = tid & 63, l15 = lane & 15, quad = lane >> 4;
;     f32x4 S[2] = {(f32x4){0.f, 0.f, 0.f, 0.f}, (f32x4){0.f, 0.f, 0.f, 0.f}};
;     *(LAS u32x4*)(Bc + (tid >> 4) * 200 + (tid & 15) * 8) = (u32x4){0u, 0u, 0u, 0u};
;     u32x4 rq0A, rq1A, rsA, rk0A, rk1A, rvA = (u32x4){0u, 0u, 0u, 0u}; f32x4 rdA;
;     u32x4 rq0B, rq1B, rsB, rk0B, rk1B, rvB = (u32x4){0u, 0u, 0u, 0u}; f32x4 rdB;
.Lp3O_entry:
	s_mov_b32 s3, s2
	s_setprio 2

; __device__ __forceinline__ void gla_scan_item(const Ctx& C, int item, LAS unsigned char* lds, int tid) {
;     ...
;     __syncthreads();
; }
.Lp3_done:
	s_setprio 0
